# v31 plus: final RMSNorm gain vectors loaded once before the row loop (were eight loads per iteration, each behind a full vmcnt(0) drain)
# speedup vs baseline: 1.0036x; 1.0010x over previous
; __device__ __forceinline__ void run_phase(const int ph, const Args& a, LAS unsigned char* lds, unsigned char* ldsg, const bool dummy = false) {
;     ...
;         } else if (EN_FIN) {
;             const float* gfin = a.in[25];
;             const int perm_ = M / ngrp;
;             for (int mi = 2 * (gj * 8 + wave); mi < perm_; mi += 2 * gsize * 8) { const int m = gx * perm_ + mi;
;                 const u32x2* hr = (const u32x2*)(HB + (size_t)m * D) + lane; u32x2 hv[8];
; #pragma unroll
;                 for (int j = 0; j < 8; ++j) hv[j] = hr[64 * j];
;                 f32x4 v[8]; float s0 = 0.f, s1 = 0.f;
; #pragma unroll
;                 for (int j = 0; j < 8; ++j) { v[j] = (f32x4){__uint_as_float(hv[j].x << 16), __uint_as_float(hv[j].x & 0xffff0000u), __uint_as_float(hv[j].y << 16), __uint_as_float(hv[j].y & 0xffff0000u)};
;                     const float q = (v[j].x * v[j].x + v[j].y * v[j].y) + (v[j].z * v[j].z + v[j].w * v[j].w); if (j < 4) s0 += q; else s1 += q; }
;                 const float r0 = __builtin_amdgcn_rsqf(wave_sum(s0) * (1.0f / 1024.0f) + 1e-6f), r1 = __builtin_amdgcn_rsqf(wave_sum(s1) * (1.0f / 1024.0f) + 1e-6f);
;                 f32x4* xr = (f32x4*)(a.out + (size_t)m * D) + lane;
; #pragma unroll
;                 for (int j = 0; j < 8; ++j) { const f32x4 gg = *((const f32x4*)gfin + lane + 64 * (j & 3)); xr[64 * j] = v[j] * (j < 4 ? r0 : r1) * gg; } }
.LBB0_2750:
	s_waitcnt lgkmcnt(0)
	s_cmp_lt_i32 s6, 16
	s_cselect_b64 s[4:5], -1, 0
	s_cmp_gt_i32 s7, 15
	s_cselect_b64 s[8:9], -1, 0
	s_and_b64 s[4:5], s[4:5], s[8:9]
	s_andn2_b64 vcc, exec, s[4:5]
	s_cbranch_vccnz .LBB0_2901
	s_and_b64 s[4:5], s[30:31], exec
	s_cselect_b32 s14, 8, 1
	v_cvt_f32_ubyte0_e32 v0, s14
	v_rcp_iflag_f32_e32 v0, v0
	s_sub_i32 s15, 0, s14
	s_abs_i32 s4, s2
	s_ashr_i32 s3, s2, 31
	v_mul_f32_e32 v0, 0x4f7ffffe, v0
	v_cvt_u32_f32_e32 v0, v0
	v_readfirstlane_b32 s6, v242
	v_readfirstlane_b32 s5, v0
	s_mul_i32 s8, s15, s5
	s_mul_hi_u32 s8, s5, s8
	s_add_i32 s5, s5, s8
	s_mul_hi_u32 s5, s4, s5
	s_mul_i32 s8, s5, s14
	s_sub_i32 s4, s4, s8
	s_add_i32 s9, s5, 1
	s_sub_i32 s8, s4, s14
	s_cmp_ge_u32 s4, s14
	s_cselect_b32 s5, s9, s5
	s_cselect_b32 s4, s8, s4
	s_add_i32 s8, s5, 1
	s_cmp_ge_u32 s4, s14
	s_cselect_b32 s4, s8, s5
	s_xor_b32 s12, s4, s3
	s_sub_i32 s16, s12, s3
	s_movk_i32 s8, 0x1000
	s_and_b64 s[4:5], s[30:31], exec
	s_cselect_b32 s8, s8, 0x8000
	s_lshr_b32 s5, s6, 5
	s_lshl_b32 s4, s16, 4
	s_and_b32 s13, s5, 0x7fffffe
	s_add_i32 s9, s4, s13
	s_cmp_ge_i32 s9, s8
	s_cbranch_scc1 .LBB0_2755
	v_readfirstlane_b32 s20, v0
	v_mbcnt_lo_u32_b32 v0, -1, 0
	v_mbcnt_hi_u32_b32 v0, -1, v0
	v_and_b32_e32 v1, 64, v0
	v_add_u32_e32 v1, 64, v1
	v_xor_b32_e32 v3, 1, v0
	v_cmp_lt_i32_e32 vcc, v3, v1
	s_mul_i32 s15, s15, s20
	s_mul_hi_u32 s15, s20, s15
	v_cndmask_b32_e32 v3, v0, v3, vcc
	v_lshlrev_b32_e32 v14, 2, v3
	v_xor_b32_e32 v3, 2, v0
	s_abs_i32 s17, s61
	s_add_i32 s20, s20, s15
	v_cmp_lt_i32_e32 vcc, v3, v1
	s_mul_hi_u32 s15, s17, s20
	s_mul_i32 s20, s15, s14
	v_cndmask_b32_e32 v3, v0, v3, vcc
	v_lshlrev_b32_e32 v15, 2, v3
	v_xor_b32_e32 v3, 4, v0
	s_mul_i32 s16, s16, s14
	s_sub_i32 s17, s17, s20
	v_cmp_lt_i32_e32 vcc, v3, v1
	s_sub_i32 s2, s2, s16
	s_ashr_i32 s16, s61, 31
	s_add_i32 s20, s15, 1
	s_sub_i32 s21, s17, s14
	v_cndmask_b32_e32 v3, v0, v3, vcc
	s_cmp_ge_u32 s17, s14
	v_lshlrev_b32_e32 v16, 2, v3
	v_xor_b32_e32 v3, 8, v0
	s_cselect_b32 s15, s20, s15
	v_cmp_lt_i32_e32 vcc, v3, v1
	s_cselect_b32 s17, s21, s17
	s_add_i32 s20, s15, 1
	v_cndmask_b32_e32 v3, v0, v3, vcc
	s_cmp_ge_u32 s17, s14
	v_lshlrev_b32_e32 v17, 2, v3
	v_xor_b32_e32 v3, 16, v0
	s_cselect_b32 s14, s20, s15
	v_cmp_lt_i32_e32 vcc, v3, v1
	s_load_dwordx4 s[4:7], s[0:1], 0xc8
	s_load_dwordx2 s[18:19], s[0:1], 0xd8
	s_xor_b32 s14, s14, s16
	v_cndmask_b32_e32 v3, v0, v3, vcc
	s_sub_i32 s16, s14, s16
	v_lshlrev_b32_e32 v18, 2, v3
	v_xor_b32_e32 v3, 32, v0
	v_and_b32_e32 v2, 63, v242
	s_and_b64 s[14:15], s[30:31], exec
	v_cmp_lt_i32_e32 vcc, v3, v1
	s_cselect_b32 s14, 12, 15
	v_lshlrev_b32_e32 v4, 4, v2
	v_cndmask_b32_e32 v0, v0, v3, vcc
	v_mov_b32_e32 v5, 0
	s_lshl_b32 s14, s2, s14
	v_lshlrev_b32_e32 v19, 2, v0
	s_waitcnt lgkmcnt(0)
	v_lshl_add_u64 v[0:1], s[4:5], 0, v[4:5]
	s_lshl_b32 s4, s12, 4
	s_add_i32 s4, s14, s4
	s_add_i32 s4, s4, s13
	s_lshl_b32 s3, s3, 4
	s_sub_i32 s12, s4, s3
	s_ashr_i32 s13, s12, 31
	s_lshl_b32 s2, s16, 4
	s_lshl_b64 s[4:5], s[12:13], 11
	s_add_u32 s4, s18, s4
	v_lshlrev_b32_e32 v2, 3, v2
	v_mov_b32_e32 v3, v5
	s_addc_u32 s5, s19, s5
	v_lshl_add_u64 v[2:3], s[4:5], 0, v[2:3]
	s_mov_b64 s[4:5], 0x6000000
	s_ashr_i32 s3, s2, 31
	v_lshl_add_u64 v[2:3], v[2:3], 0, s[4:5]
	s_lshl_b64 s[4:5], s[2:3], 11
	s_lshl_b64 s[12:13], s[12:13], 12
	s_add_u32 s6, s6, s12
	s_addc_u32 s7, s7, s13
	v_lshl_add_u64 v[4:5], s[6:7], 0, v[4:5]
	s_mov_b64 s[6:7], 0x1000
	v_lshl_add_u64 v[4:5], v[4:5], 0, s[6:7]
	s_lshl_b64 s[6:7], s[2:3], 12
	v_mov_b32_e32 v20, 0x358637bd
	global_load_dwordx4 v[60:63], v[0:1], off
	global_load_dwordx4 v[64:67], v[0:1], off offset:1024
	global_load_dwordx4 v[68:71], v[0:1], off offset:2048
	global_load_dwordx4 v[72:75], v[0:1], off offset:3072
.LBB0_2753:
	global_load_dwordx2 v[26:27], v[2:3], off
	global_load_dwordx2 v[28:29], v[2:3], off offset:512
	global_load_dwordx2 v[30:31], v[2:3], off offset:1024
	global_load_dwordx2 v[32:33], v[2:3], off offset:1536
	global_load_dwordx2 v[12:13], v[2:3], off offset:2048
	global_load_dwordx2 v[10:11], v[2:3], off offset:2560
	global_load_dwordx2 v[8:9], v[2:3], off offset:3072
	global_load_dwordx2 v[6:7], v[2:3], off offset:3584
	s_add_i32 s9, s9, s2
	v_lshl_add_u64 v[2:3], v[2:3], 0, s[4:5]
	s_cmp_lt_i32 s9, s8
	s_waitcnt vmcnt(7)
	v_lshlrev_b32_e32 v34, 16, v26
	v_and_b32_e32 v35, 0xffff0000, v26
	v_lshlrev_b32_e32 v26, 16, v27
	v_and_b32_e32 v27, 0xffff0000, v27
	s_waitcnt vmcnt(6)
	v_lshlrev_b32_e32 v37, 16, v29
	v_lshlrev_b32_e32 v36, 16, v28
	v_and_b32_e32 v29, 0xffff0000, v29
	v_and_b32_e32 v28, 0xffff0000, v28
	s_waitcnt vmcnt(5)
	v_and_b32_e32 v39, 0xffff0000, v30
	s_waitcnt vmcnt(4)
	v_lshlrev_b32_e32 v41, 16, v32
	v_and_b32_e32 v43, 0xffff0000, v32
	v_mul_f32_e32 v40, v27, v27
	v_mul_f32_e32 v42, v35, v35
	v_lshlrev_b32_e32 v38, 16, v30
	v_lshlrev_b32_e32 v30, 16, v31
	v_and_b32_e32 v31, 0xffff0000, v31
	v_pk_mul_f32 v[44:45], v[28:29], v[28:29]
	v_mov_b32_e32 v47, v41
	v_mul_f32_e32 v46, v39, v39
	v_pk_fma_f32 v[50:51], v[26:27], v[26:27], v[40:41] op_sel_hi:[1,1,0]
	v_pk_fma_f32 v[52:53], v[34:35], v[34:35], v[42:43] op_sel_hi:[1,1,0]
	v_lshlrev_b32_e32 v32, 16, v33
	v_and_b32_e32 v33, 0xffff0000, v33
	v_mul_f32_e32 v48, v31, v31
	v_pk_fma_f32 v[44:45], v[36:37], v[36:37], v[44:45]
	v_pk_fma_f32 v[54:55], v[38:39], v[38:39], v[46:47] op_sel_hi:[1,1,0]
	v_mov_b32_e32 v40, v52
	v_mov_b32_e32 v46, v50
	v_mul_f32_e32 v21, v43, v43
	v_mul_f32_e32 v56, v32, v32
	v_mul_f32_e32 v57, v33, v33
	v_pk_fma_f32 v[48:49], v[30:31], v[30:31], v[48:49] op_sel_hi:[1,1,0]
	v_pk_add_f32 v[50:51], v[52:53], v[50:51]
	v_pk_add_f32 v[44:45], v[44:45], v[44:45] op_sel:[0,1] op_sel_hi:[1,0]
	v_pk_mul_f32 v[46:47], v[40:41], v[46:47]
	v_mov_b32_e32 v55, v56
	v_mov_b32_e32 v49, v57
	v_mov_b32_e32 v45, v21
	v_mov_b32_e32 v51, v47
	v_pk_add_f32 v[48:49], v[54:55], v[48:49]
	v_pk_add_f32 v[44:45], v[50:51], v[44:45]
	v_mov_b32_e32 v42, v41
	v_pk_add_f32 v[44:45], v[44:45], v[48:49]
	s_nop 0
	v_add_f32_e32 v21, v44, v45
	ds_bpermute_b32 v40, v14, v21
	s_waitcnt lgkmcnt(0)
; __device__ __forceinline__ void run_phase(const int ph, const Args& a, LAS unsigned char* lds, unsigned char* ldsg, const bool dummy = false) {
;     ...
;                     const float q = (v[j].x * v[j].x + v[j].y * v[j].y) + (v[j].z * v[j].z + v[j].w * v[j].w); if (j < 4) s0 += q; else s1 += q; }
;                 const float r0 = __builtin_amdgcn_rsqf(wave_sum(s0) * (1.0f / 1024.0f) + 1e-6f), r1 = __builtin_amdgcn_rsqf(wave_sum(s1) * (1.0f / 1024.0f) + 1e-6f);
;                 f32x4* xr = (f32x4*)(a.out + (size_t)m * D) + lane;
; #pragma unroll
;                 for (int j = 0; j < 8; ++j) { const f32x4 gg = *((const f32x4*)gfin + lane + 64 * (j & 3)); xr[64 * j] = v[j] * (j < 4 ? r0 : r1) * gg; } }
	v_add_f32_e32 v21, v21, v40
	ds_bpermute_b32 v40, v15, v21
	s_waitcnt lgkmcnt(0)
	v_add_f32_e32 v21, v21, v40
	ds_bpermute_b32 v40, v16, v21
	s_waitcnt lgkmcnt(0)
	v_add_f32_e32 v21, v21, v40
	ds_bpermute_b32 v40, v17, v21
	s_waitcnt lgkmcnt(0)
	v_add_f32_e32 v21, v21, v40
	ds_bpermute_b32 v40, v18, v21
	s_waitcnt lgkmcnt(0)
	v_add_f32_e32 v21, v21, v40
	ds_bpermute_b32 v40, v19, v21
	s_waitcnt lgkmcnt(0)
	v_add_f32_e32 v21, v21, v40
	v_fmamk_f32 v21, v21, 0x3a800000, v20
	v_rsq_f32_e32 v40, v21
	s_nop 0
	v_pk_mul_f32 v[34:35], v[40:41], v[34:35] op_sel_hi:[0,1]
	v_pk_mul_f32 v[26:27], v[40:41], v[26:27] op_sel_hi:[0,1]
	s_waitcnt vmcnt(0)
	v_pk_mul_f32 v[24:25], v[62:63], v[26:27]
	v_pk_mul_f32 v[22:23], v[60:61], v[34:35]
	global_store_dwordx4 v[4:5], v[22:25], off offset:-4096
	v_mov_b32_e32 v26, v37
	v_mov_b32_e32 v27, v29
	v_mov_b32_e32 v37, v28
	v_pk_mul_f32 v[26:27], v[40:41], v[26:27] op_sel_hi:[0,1]
	v_pk_mul_f32 v[28:29], v[40:41], v[36:37] op_sel_hi:[0,1]
	v_lshlrev_b32_e32 v34, 16, v8
	v_and_b32_e32 v35, 0xffff0000, v8
	v_lshlrev_b32_e32 v36, 16, v9
	v_and_b32_e32 v37, 0xffff0000, v9
	v_pk_mul_f32 v[8:9], v[42:43], v[40:41] op_sel_hi:[1,0]
	v_pk_mul_f32 v[22:23], v[28:29], v[64:65]
	v_pk_mul_f32 v[24:25], v[26:27], v[66:67]
	global_store_dwordx4 v[4:5], v[22:25], off offset:-3072
	v_pk_mul_f32 v[26:27], v[40:41], v[30:31] op_sel_hi:[0,1]
	v_pk_mul_f32 v[28:29], v[40:41], v[38:39] op_sel_hi:[0,1]
	v_and_b32_e32 v31, 0xffff0000, v11
	v_and_b32_e32 v30, 0xffff0000, v10
	v_pk_mul_f32 v[38:39], v[30:31], v[30:31]
	v_pk_mul_f32 v[22:23], v[28:29], v[68:69]
	v_pk_mul_f32 v[24:25], v[26:27], v[70:71]
	global_store_dwordx4 v[4:5], v[22:25], off offset:-2048
	v_lshlrev_b32_e32 v29, 16, v11
	v_lshlrev_b32_e32 v28, 16, v10
	v_pk_mul_f32 v[10:11], v[32:33], v[40:41] op_sel_hi:[1,0]
	v_lshlrev_b32_e32 v26, 16, v12
	v_and_b32_e32 v27, 0xffff0000, v12
	v_lshlrev_b32_e32 v12, 16, v13
	v_and_b32_e32 v13, 0xffff0000, v13
	v_lshlrev_b32_e32 v32, 16, v7
	v_and_b32_e32 v33, 0xffff0000, v7
	v_mul_f32_e32 v40, v37, v37
	v_pk_fma_f32 v[38:39], v[28:29], v[28:29], v[38:39]
	v_mul_f32_e32 v48, v32, v32
	v_mul_f32_e32 v49, v33, v33
	v_pk_fma_f32 v[40:41], v[36:37], v[36:37], v[40:41] op_sel_hi:[1,1,0]
	v_pk_add_f32 v[38:39], v[38:39], v[38:39] op_sel:[0,1] op_sel_hi:[1,0]
	v_mov_b32_e32 v41, v49
	v_pk_mul_f32 v[8:9], v[8:9], v[72:73]
	v_pk_mul_f32 v[10:11], v[10:11], v[74:75]
	global_store_dwordx4 v[4:5], v[8:11], off offset:-1024
	v_lshlrev_b32_e32 v23, 16, v6
	v_and_b32_e32 v25, 0xffff0000, v6
	v_mul_f32_e32 v6, v13, v13
	v_mul_f32_e32 v22, v27, v27
	v_mov_b32_e32 v7, v23
	v_pk_fma_f32 v[42:43], v[12:13], v[12:13], v[6:7] op_sel_hi:[1,1,0]
	v_pk_fma_f32 v[44:45], v[26:27], v[26:27], v[22:23] op_sel_hi:[1,1,0]
	v_mul_f32_e32 v24, v35, v35
	v_mov_b32_e32 v22, v44
	v_mov_b32_e32 v6, v42
	v_mul_f32_e32 v21, v25, v25
	v_pk_fma_f32 v[46:47], v[34:35], v[34:35], v[24:25] op_sel_hi:[1,1,0]
	v_pk_add_f32 v[42:43], v[44:45], v[42:43]
	v_pk_mul_f32 v[6:7], v[22:23], v[6:7]
	v_mov_b32_e32 v47, v48
	v_mov_b32_e32 v39, v21
	v_mov_b32_e32 v43, v7
	v_pk_add_f32 v[40:41], v[46:47], v[40:41]
	v_pk_add_f32 v[6:7], v[42:43], v[38:39]
	v_mov_b32_e32 v24, v23
	v_pk_add_f32 v[6:7], v[6:7], v[40:41]
	s_nop 0
	v_add_f32_e32 v6, v6, v7
	ds_bpermute_b32 v7, v14, v6
	s_waitcnt lgkmcnt(0)
	v_add_f32_e32 v6, v6, v7
	ds_bpermute_b32 v7, v15, v6
	s_waitcnt lgkmcnt(0)
	v_add_f32_e32 v6, v6, v7
	ds_bpermute_b32 v7, v16, v6
	s_waitcnt lgkmcnt(0)
	v_add_f32_e32 v6, v6, v7
	ds_bpermute_b32 v7, v17, v6
	s_waitcnt lgkmcnt(0)
	v_add_f32_e32 v6, v6, v7
	ds_bpermute_b32 v7, v18, v6
	s_waitcnt lgkmcnt(0)
	v_add_f32_e32 v6, v6, v7
	ds_bpermute_b32 v7, v19, v6
	s_waitcnt lgkmcnt(0)
	v_add_f32_e32 v6, v6, v7
	v_fmamk_f32 v6, v6, 0x3a800000, v20
	v_rsq_f32_e32 v22, v6
	s_nop 0
	v_pk_mul_f32 v[12:13], v[22:23], v[12:13] op_sel_hi:[0,1]
	v_pk_mul_f32 v[6:7], v[22:23], v[26:27] op_sel_hi:[0,1]
	v_pk_mul_f32 v[6:7], v[6:7], v[60:61]
	v_pk_mul_f32 v[8:9], v[12:13], v[62:63]
	global_store_dwordx4 v[4:5], v[6:9], off
	v_mov_b32_e32 v10, v29
	v_mov_b32_e32 v11, v31
	v_mov_b32_e32 v29, v30
	v_pk_mul_f32 v[10:11], v[22:23], v[10:11] op_sel_hi:[0,1]
	v_pk_mul_f32 v[12:13], v[22:23], v[28:29] op_sel_hi:[0,1]
	v_pk_mul_f32 v[6:7], v[12:13], v[64:65]
	v_pk_mul_f32 v[8:9], v[10:11], v[66:67]
	global_store_dwordx4 v[4:5], v[6:9], off offset:1024
	v_pk_mul_f32 v[10:11], v[22:23], v[36:37] op_sel_hi:[0,1]
	v_pk_mul_f32 v[12:13], v[22:23], v[34:35] op_sel_hi:[0,1]
	v_pk_mul_f32 v[6:7], v[12:13], v[68:69]
	v_pk_mul_f32 v[8:9], v[10:11], v[70:71]
	global_store_dwordx4 v[4:5], v[6:9], off offset:2048
	v_pk_mul_f32 v[10:11], v[32:33], v[22:23] op_sel_hi:[1,0]
	v_pk_mul_f32 v[12:13], v[24:25], v[22:23] op_sel_hi:[1,0]
	v_pk_mul_f32 v[8:9], v[10:11], v[74:75]
	v_pk_mul_f32 v[6:7], v[12:13], v[72:73]
	global_store_dwordx4 v[4:5], v[6:9], off offset:3072
	v_lshl_add_u64 v[4:5], v[4:5], 0, s[6:7]
	s_cbranch_scc1 .LBB0_2753
	s_load_dword s7, s[0:1], 0xe4
